# P3: static s_setprio 1 for the one critical wave of each SIMD (waves 0,1 for the two-block steps, 6,7 for the T step)
# speedup vs baseline: 1.0100x; 1.0083x over previous
.LBB0_585:
	v_readlane_b32 s0, v255, 2
	v_readlane_b32 s1, v255, 3
	s_mov_b64 s[4:5], s[0:1]
	s_cmp_lt_i32 s4, 4
	v_readlane_b32 s2, v255, 4
	v_readlane_b32 s3, v255, 5
	s_cselect_b64 s[0:1], -1, 0
	s_cmp_gt_i32 s5, 3
	s_cselect_b64 s[2:3], -1, 0
	s_and_b64 s[0:1], s[0:1], s[2:3]
	v_writelane_b32 v255, s0, 9
	s_andn2_b64 vcc, exec, s[0:1]
	s_nop 0
	v_writelane_b32 v255, s1, 10
	s_cbranch_vccnz .LBB0_617
	s_mov_b64 s[2:3], s[74:75]
	v_mov_b32_e32 v1, v0
	s_cmpk_gt_i32 s84, 0xff
	s_cbranch_scc1 .LBB0_617
	v_readfirstlane_b32 s98, v0
	s_nop 1
	s_lshr_b32 s98, s98, 6
	s_add_u32 s98, s98, 2
	s_and_b32 s98, s98, 7
	s_cmp_lt_u32 s98, 4
	s_cbranch_scc0 .Lmy_p3_noprio
	s_setprio 1
